# scan: waves 4-7 issue the next chunk's loads right after QK^T (before the 2nd barrier) instead of at the step tail
# speedup vs baseline: 1.0322x; 1.0036x over previous
.LBB0_1161:
	v_lshl_add_u64 v[2:3], v[2:3], 1, s[70:71]
	s_lshl_b64 s[44:45], s[48:49], 1
	global_load_dwordx2 v[164:165], v[2:3], off
	global_load_dwordx2 v[166:167], v[2:3], off offset:16
	v_lshl_add_u64 v[2:3], v[152:153], 0, s[44:45]
	v_lshl_add_u64 v[4:5], v[154:155], 0, s[44:45]
	global_load_dwordx4 v[128:131], v[2:3], off
	global_load_dwordx4 v[132:135], v[4:5], off
	s_cmp_lg_u64 s[8:9], 0
	s_cbranch_scc1 .LBB0_1162
	s_and_b64 vcc, exec, s[82:83]
	s_cbranch_vccnz .Lscan_b2
	s_branch .Lscan_loads_ret

.LBB0_1169:
	s_or_b64 exec, exec, s[44:45]
	s_cmp_lg_u64 s[8:9], 0
	s_cbranch_scc1 .Lscan_b2
	s_cmp_eq_u32 s89, -1
	s_cbranch_scc1 .Lscan_b2
	s_branch .Lscan_loads
.Lscan_b2:
	s_waitcnt lgkmcnt(0)
	s_barrier
	s_and_saveexec_b64 s[44:45], s[8:9]
	s_cbranch_execz .LBB0_1171
	v_add_u32_e32 v0, v180, v192
	ds_read_b128 v[2:5], v0 offset:49152
	v_add_u32_e32 v0, v182, v192
	ds_read_b128 v[12:15], v0
	ds_read_b128 v[112:115], v0 offset:4096
	v_add_u32_e32 v0, v180, v193
	ds_read_b128 v[116:119], v0 offset:49152
	v_add_u32_e32 v0, v182, v193
	ds_read_b128 v[120:123], v0
	ds_read_b128 v[124:127], v0 offset:4096
	s_ashr_i32 s81, s80, 31
	s_lshl_b64 s[60:61], s[80:81], 11
	s_waitcnt lgkmcnt(4)
	v_mfma_f32_32x32x16_bf16 v[80:95], v[2:5], v[12:15], v[80:95]
	s_waitcnt lgkmcnt(3)
	v_mfma_f32_32x32x16_bf16 v[96:111], v[2:5], v[112:115], v[96:111]
	v_add_u32_e32 v0, v180, v195
	ds_read_b128 v[2:5], v0 offset:49152
	v_add_u32_e32 v0, v182, v195
	ds_read_b128 v[12:15], v0
	ds_read_b128 v[112:115], v0 offset:4096
	s_waitcnt lgkmcnt(4)
	v_mfma_f32_32x32x16_bf16 v[80:95], v[116:119], v[120:123], v[80:95]
	s_waitcnt lgkmcnt(3)
	v_mfma_f32_32x32x16_bf16 v[96:111], v[116:119], v[124:127], v[96:111]
	v_add_u32_e32 v0, v180, v196
	ds_read_b128 v[116:119], v0 offset:49152
	v_add_u32_e32 v0, v182, v196
	ds_read_b128 v[120:123], v0
	ds_read_b128 v[124:127], v0 offset:4096
	s_waitcnt lgkmcnt(4)
	v_mfma_f32_32x32x16_bf16 v[80:95], v[2:5], v[12:15], v[80:95]
	s_waitcnt lgkmcnt(3)
	v_mfma_f32_32x32x16_bf16 v[96:111], v[2:5], v[112:115], v[96:111]
	s_waitcnt lgkmcnt(1)
	v_mfma_f32_32x32x16_bf16 v[80:95], v[116:119], v[120:123], v[80:95]
	s_waitcnt lgkmcnt(0)
	v_mfma_f32_32x32x16_bf16 v[96:111], v[116:119], v[124:127], v[96:111]
	v_mbcnt_lo_u32_b32 v0, -1, 0
	v_mbcnt_hi_u32_b32 v0, -1, v0
	v_and_b32_e32 v120, 31, v0
	v_lshrrev_b32_e32 v121, 5, v0
	v_mul_u32_u24_e32 v120, 0x7fe, v120
	v_mul_u32_u24_e32 v121, 0x1ff0, v121
	v_sub_u32_e32 v120, v120, v121
	v_ashrrev_i32_e32 v121, 31, v120
	v_lshl_add_u64 v[124:125], v[168:169], 0, v[120:121]
	v_lshl_add_u64 v[124:125], v[124:125], 0, s[60:61]
	s_mov_b64 s[60:61], 0x10000
	v_lshl_add_u64 v[126:127], v[124:125], 0, s[60:61]
	s_nop 3
	v_cvt_pk_bf16_f32 v2, v80, v81
	v_cvt_pk_bf16_f32 v3, v82, v83
	v_cvt_pk_bf16_f32 v4, v84, v85
	v_cvt_pk_bf16_f32 v5, v86, v87
	s_nop 1
	v_permlane32_swap_b32_e32 v2, v4
	v_permlane32_swap_b32_e32 v3, v5
	global_store_dwordx4 v[124:125], v[2:5], off
	v_cvt_pk_bf16_f32 v12, v88, v89
	v_cvt_pk_bf16_f32 v13, v90, v91
	v_cvt_pk_bf16_f32 v14, v92, v93
	v_cvt_pk_bf16_f32 v15, v94, v95
	s_nop 1
	v_permlane32_swap_b32_e32 v12, v14
	v_permlane32_swap_b32_e32 v13, v15
	global_store_dwordx4 v[124:125], v[12:15], off offset:32
	v_cvt_pk_bf16_f32 v112, v96, v97
	v_cvt_pk_bf16_f32 v113, v98, v99
	v_cvt_pk_bf16_f32 v114, v100, v101
	v_cvt_pk_bf16_f32 v115, v102, v103
	s_nop 1
	v_permlane32_swap_b32_e32 v112, v114
	v_permlane32_swap_b32_e32 v113, v115
	global_store_dwordx4 v[126:127], v[112:115], off
	v_cvt_pk_bf16_f32 v116, v104, v105
	v_cvt_pk_bf16_f32 v117, v106, v107
	v_cvt_pk_bf16_f32 v118, v108, v109
	v_cvt_pk_bf16_f32 v119, v110, v111
	s_nop 1
	v_permlane32_swap_b32_e32 v116, v118
	v_permlane32_swap_b32_e32 v117, v119
	global_store_dwordx4 v[126:127], v[116:119], off offset:32

.LBB0_1172:
	s_cmp_lg_u64 s[8:9], 0
	s_cbranch_scc1 .Lscan_tail_w03
	s_and_b64 vcc, exec, s[82:83]
	s_cbranch_vccnz .Lscan_tail_w03
	s_cmp_eq_u32 s89, -1
	s_cbranch_scc1 .Lscan_tail_w03
	s_branch .Lscan_loads
